# v61 + FoX step loop VALU trimming: decay-bias init as 16 v_pk_add (neg) instead of 32 v_sub, V^T fragment offsets precomputed per unit (16 adds per tile instead of 28)
# baseline (speedup 1.0000x reference)
; template <bool MOBA>
; __device__ __forceinline__ void attn_unit(unsigned char* lds, LAS unsigned char* lds3, const Params& p, int b, int h, int qb) {
;     ...
;         float sq[2] = {0.f, 0.f};
; #pragma unroll
;         for (int jb = 0; jb < 2; ++jb)
; #pragma unroll
;             for (int ks = 0; ks < 2; ++ks) { const u32x4 qv = __builtin_bit_cast(u32x4, qf[jb][ks]);
; #pragma unroll
;                 for (int j = 0; j < 4; ++j) { const float a = bf_lo(qv[j]), c = bf_hi(qv[j]); sq[jb] += a * a + c * c; } }
;         const float kall = kpms[NT - 1];
; #pragma unroll
;         for (int jb = 0; jb < 2; ++jb) { float v = sq[jb]; v += __shfl_xor(v, 16); v += __shfl_xor(v, 32); mref[jb] = sqrtf(v) * 1.002f * kall + (MOBA ? bmax : 0.f); }
.LBB0_530:
	s_mov_b32 s88, 0xfffc0000
	s_mov_b32 s89, -1
	s_or_b64 exec, exec, s[10:11]
	s_waitcnt vmcnt(3)
	v_and_b32_e32 v41, 0xffff0000, v6
	v_lshlrev_b32_e32 v40, 16, v6
	v_mul_f32_e32 v41, v41, v41
	v_and_b32_e32 v43, 0xffff0000, v7
	v_fmac_f32_e32 v41, v40, v40
	v_lshlrev_b32_e32 v40, 16, v7
	v_mul_f32_e32 v43, v43, v43
	v_fmac_f32_e32 v43, v40, v40
	v_add_f32_e32 v40, v43, v41
	v_and_b32_e32 v43, 0xffff0000, v8
	v_lshlrev_b32_e32 v41, 16, v8
	v_mul_f32_e32 v43, v43, v43
	v_fmac_f32_e32 v43, v41, v41
	v_add_f32_e32 v40, v43, v40
	v_and_b32_e32 v43, 0xffff0000, v9
	v_lshlrev_b32_e32 v41, 16, v9
	v_mul_f32_e32 v43, v43, v43
	v_fmac_f32_e32 v43, v41, v41
	s_waitcnt vmcnt(2)
	v_and_b32_e32 v47, 0xffff0000, v11
	v_and_b32_e32 v46, 0xffff0000, v10
	v_add_f32_e32 v43, v43, v40
	v_lshlrev_b32_e32 v41, 16, v11
	v_lshlrev_b32_e32 v40, 16, v10
	v_pk_mul_f32 v[46:47], v[46:47], v[46:47]
	v_xor_b32_e32 v49, 32, v225
	v_pk_fma_f32 v[40:41], v[40:41], v[40:41], v[46:47]
	v_and_b32_e32 v47, 0xffff0000, v13
	v_add_f32_e32 v40, v40, v43
	v_and_b32_e32 v46, 0xffff0000, v12
	v_add_f32_e32 v43, v41, v40
	v_lshlrev_b32_e32 v41, 16, v13
	v_lshlrev_b32_e32 v40, 16, v12
	v_pk_mul_f32 v[46:47], v[46:47], v[46:47]
	s_lshl_b32 s8, s21, 2
	v_pk_fma_f32 v[40:41], v[40:41], v[40:41], v[46:47]
	s_waitcnt vmcnt(1)
	v_and_b32_e32 v46, 0xffff0000, v19
	v_add_f32_e32 v40, v40, v43
	v_add_f32_e32 v43, v41, v40
	v_and_b32_e32 v41, 0xffff0000, v18
	v_lshlrev_b32_e32 v40, 16, v18
	v_mul_f32_e32 v41, v41, v41
	v_fmac_f32_e32 v41, v40, v40
	v_lshlrev_b32_e32 v40, 16, v19
	v_mul_f32_e32 v46, v46, v46
	v_fmac_f32_e32 v46, v40, v40
	v_add_f32_e32 v40, v46, v41
	v_and_b32_e32 v46, 0xffff0000, v20
	v_lshlrev_b32_e32 v41, 16, v20
	v_mul_f32_e32 v46, v46, v46
	v_fmac_f32_e32 v46, v41, v41
	v_add_f32_e32 v40, v46, v40
	v_and_b32_e32 v46, 0xffff0000, v21
	v_lshlrev_b32_e32 v41, 16, v21
	v_mul_f32_e32 v46, v46, v46
	v_fmac_f32_e32 v46, v41, v41
	v_add_f32_e32 v48, v46, v40
	s_waitcnt vmcnt(0)
	v_and_b32_e32 v47, 0xffff0000, v23
	v_and_b32_e32 v46, 0xffff0000, v22
	v_lshlrev_b32_e32 v41, 16, v23
	v_lshlrev_b32_e32 v40, 16, v22
	v_pk_mul_f32 v[46:47], v[46:47], v[46:47]
	s_add_i32 s8, s8, 0
	v_pk_fma_f32 v[40:41], v[40:41], v[40:41], v[46:47]
	v_and_b32_e32 v47, 0xffff0000, v25
	v_add_f32_e32 v40, v40, v48
	v_and_b32_e32 v46, 0xffff0000, v24
	v_add_f32_e32 v48, v41, v40
	v_lshlrev_b32_e32 v41, 16, v25
	v_lshlrev_b32_e32 v40, 16, v24
	v_pk_mul_f32 v[46:47], v[46:47], v[46:47]
	s_lshl_b32 s9, s7, 2
	v_pk_fma_f32 v[40:41], v[40:41], v[40:41], v[46:47]
	v_and_b32_e32 v47, 64, v225
	v_xor_b32_e32 v46, 16, v225
	v_add_u32_e32 v47, 64, v47
	v_cmp_lt_i32_e32 vcc, v46, v47
	v_add_f32_e32 v40, v40, v48
	v_add_f32_e32 v40, v41, v40
	v_cndmask_b32_e32 v46, v225, v46, vcc
	v_lshlrev_b32_e32 v117, 2, v46
	ds_bpermute_b32 v46, v117, v43
	v_cmp_lt_i32_e32 vcc, v49, v47
	s_add_i32 s8, s8, s9
	s_add_i32 s8, s8, 0x12000
	v_cndmask_b32_e32 v47, v225, v49, vcc
	v_lshlrev_b32_e32 v118, 2, v47
	s_waitcnt lgkmcnt(0)
	v_add_f32_e32 v43, v43, v46
	ds_bpermute_b32 v46, v118, v43
	v_mov_b32_e32 v36, s8
	v_lshl_add_u32 v38, v1, 2, s8
	s_lshl_b32 s6, s6, 2
	s_add_i32 s6, s6, 0
	s_waitcnt lgkmcnt(0)
	v_add_f32_e32 v41, v43, v46
	v_mul_f32_e32 v43, 0x4f800000, v41
	v_cmp_gt_f32_e32 vcc, s60, v41
	s_add_i32 s6, s6, 0x16800
	v_mov_b32_e32 v46, s6
	v_cndmask_b32_e32 v41, v41, v43, vcc
	v_sqrt_f32_e32 v43, v41
	s_barrier
; #define LAS __attribute__((address_space(3)))
; template <bool MOBA>
; __device__ __forceinline__ void attn_unit(unsigned char* lds, LAS unsigned char* lds3, const Params& p, int b, int h, int qb) {
;     ...
;     f32x4 o[4][2];
; #pragma unroll
;     for (int db = 0; db < 4; ++db) { o[db][0] = (f32x4){0.f, 0.f, 0.f, 0.f}; o[db][1] = (f32x4){0.f, 0.f, 0.f, 0.f}; }
;     float lrow[2] = {0.f, 0.f};
;     float fq2[2] = {0.f, 0.f}; unsigned selm[2] = {0u, 0u};
;     if (!MOBA) { fq2[0] = Fs[qb * 256 + 32 * w + fr]; fq2[1] = Fs[qb * 256 + 32 * w + 16 + fr]; }
;     else { selm[0] = sel[32 * w + fr]; selm[1] = sel[32 * w + 16 + fr]; }
;     const int qloc = 32 * w + fr;
;     float mref[2], fq0 = 0.f; bool wdone = false;
;     {
;         float sq[2] = {0.f, 0.f};
; #pragma unroll
;         for (int jb = 0; jb < 2; ++jb)
; #pragma unroll
;             for (int ks = 0; ks < 2; ++ks) { const u32x4 qv = __builtin_bit_cast(u32x4, qf[jb][ks]);
; #pragma unroll
;                 for (int j = 0; j < 4; ++j) { const float a = bf_lo(qv[j]), c = bf_hi(qv[j]); sq[jb] += a * a + c * c; } }
;         const float kall = kpms[NT - 1];
; #pragma unroll
;         for (int jb = 0; jb < 2; ++jb) { float v = sq[jb]; v += __shfl_xor(v, 16); v += __shfl_xor(v, 32); mref[jb] = sqrtf(v) * 1.002f * kall + (MOBA ? bmax : 0.f); }
;         if (!MOBA) fq0 = Fs[qb * 256 + 32 * w];
;     }
;     LAS unsigned char* listq = (LAS unsigned char*)(lds3 + 80000); LAS unsigned char* cntw = (LAS unsigned char*)(lds3 + 85120); LAS int* njs = (LAS int*)(lds3 + 85248); LAS float* mrefs = (LAS float*)(lds3 + 84096); LAS float* pst = (LAS float*)(lds3 + 93184);
;     int qpl[2] = {qloc, qloc + 16}; bool qv[2] = {true, true}; float mrc[2] = {mref[0], mref[1]};
;     ...
;                 for (int db = 0; db < 4; ++db) { const int d = 32 * (db >> 1) + 8 * (fr >> 2) + 4 * (db & 1) + (fr & 3);        const int kx = (32 * ks2 + 4 * fq) ^ (((d >> 3) & 7) << 3);
;                     vlo[ks2][db] = *(const LAS u32x2*)(Vt + slot * 4608 + d * 72 + kx); vhi[ks2][db] = *(const LAS u32x2*)(Vt + slot * 4608 + d * 72 + (kx ^ 16)); }
	v_add_u32_e32 v47, -1, v43
	v_fma_f32 v48, -v47, v43, v41
	v_cmp_ge_f32_e64 s[8:9], 0, v48
	ds_bpermute_b32 v48, v117, v40
	v_add_u32_e32 v49, 1, v43
	v_cndmask_b32_e64 v47, v43, v47, s[8:9]
	v_fma_f32 v43, -v49, v43, v41
	v_cmp_lt_f32_e64 s[8:9], 0, v43
	s_waitcnt lgkmcnt(0)
	v_add_f32_e32 v40, v40, v48
	ds_read_b32 v46, v46
	ds_read_b32 v119, v36
	v_cndmask_b32_e64 v43, v47, v49, s[8:9]
	ds_bpermute_b32 v47, v118, v40
	v_mul_f32_e32 v48, 0x37800000, v43
	v_cndmask_b32_e32 v43, v43, v48, vcc
	v_cmp_class_f32_e32 vcc, v41, v224
	s_ashr_i32 s4, s4, 7
	s_waitcnt lgkmcnt(0)
	v_add_f32_e32 v40, v40, v47
	v_cndmask_b32_e32 v41, v43, v41, vcc
	v_mul_f32_e32 v43, 0x4f800000, v40
	v_cmp_gt_f32_e32 vcc, s60, v40
	v_mul_f32_e32 v41, 0x3f804189, v41
	v_fma_f32 v36, v46, v41, 0
	v_cndmask_b32_e32 v40, v40, v43, vcc
	v_sqrt_f32_e32 v43, v40
	v_mul_u32_u24_e32 v121, 0x90, v1
	s_lshl_b32 s83, s5, 1
	s_lshl_b32 s5, s20, 2
	v_add_u32_e32 v41, -1, v43
	v_fma_f32 v47, -v41, v43, v40
	v_cmp_ge_f32_e64 s[8:9], 0, v47
	v_add_u32_e32 v47, 1, v43
	v_and_b32_e32 v49, 3, v42
	v_cndmask_b32_e64 v41, v43, v41, s[8:9]
	v_fma_f32 v43, -v47, v43, v40
	v_cmp_lt_f32_e64 s[8:9], 0, v43
	s_add_i32 s91, s5, 0
	s_mov_b32 s87, s75
	v_cndmask_b32_e64 v41, v41, v47, s[8:9]
	v_mul_f32_e32 v43, 0x37800000, v41
	v_cndmask_b32_e32 v41, v41, v43, vcc
	v_cmp_class_f32_e32 vcc, v40, v224
	v_lshlrev_b32_e32 v43, 2, v37
	v_lshlrev_b32_e32 v47, 1, v1
	v_cndmask_b32_e32 v40, v41, v40, vcc
	v_mul_f32_e32 v40, 0x3f804189, v40
	v_fma_f32 v40, v46, v40, 0
	v_or_b32_e32 v46, s7, v1
	v_lshl_or_b32 v1, s4, 6, v43
	v_or_b32_e32 v50, 2, v1
	v_or_b32_e32 v52, 16, v46
	v_cmp_gt_i32_e64 s[14:15], v50, v46
	v_or_b32_e32 v51, 3, v1
	v_cmp_gt_i32_e64 s[22:23], v50, v52
	v_or_b32_e32 v50, 16, v1
	v_cmp_gt_i32_e64 s[16:17], v51, v46
	v_cmp_gt_i32_e64 s[24:25], v51, v52
	v_cmp_gt_i32_e64 s[26:27], v50, v46
	v_or_b32_e32 v50, 17, v1
	v_or_b32_e32 v51, 18, v1
	v_or_b32_e32 v53, 19, v1
	v_cmp_gt_i32_e64 s[28:29], v50, v46
	v_cmp_gt_i32_e64 s[30:31], v51, v46
	v_cmp_gt_i32_e64 s[34:35], v53, v46
	v_cmp_gt_i32_e64 s[36:37], v50, v52
	v_cmp_gt_i32_e64 s[38:39], v51, v52
	v_cmp_gt_i32_e64 s[40:41], v53, v52
	v_or_b32_e32 v50, 32, v1
	v_or_b32_e32 v51, 33, v1
	v_or_b32_e32 v53, 34, v1
	v_and_b32_e32 v48, 24, v47
	v_cmp_gt_i32_e64 s[10:11], v1, v46
	v_cmp_lt_i32_e64 s[12:13], v1, v46
	v_cmp_gt_i32_e64 s[18:19], v1, v52
	v_cmp_lt_i32_e64 s[20:21], v1, v52
	v_cmp_gt_i32_e64 s[42:43], v50, v46
	v_cmp_gt_i32_e64 s[44:45], v51, v46
	v_cmp_gt_i32_e64 s[46:47], v53, v46
	v_or_b32_e32 v54, 35, v1
	v_cmp_gt_i32_e64 s[50:51], v50, v52
	v_cmp_gt_i32_e64 s[52:53], v51, v52
	v_cmp_gt_i32_e64 s[54:55], v53, v52
	v_or_b32_e32 v50, 48, v1
	v_or_b32_e32 v51, 49, v1
	v_or_b32_e32 v53, 50, v1
	v_or_b32_e32 v1, 51, v1
	v_cmp_gt_i32_e64 s[64:65], v1, v46
	v_cmp_gt_i32_e64 s[72:73], v1, v52
	v_or_b32_e32 v1, v48, v49
	s_add_i32 s91, s91, 0x16a00
	v_mul_u32_u24_e32 v123, 0x90, v1
	v_or_b32_e32 v1, 4, v49
	s_lshl_b64 s[6:7], s[86:87], 19
	v_cmp_gt_i32_e64 s[48:49], v54, v46
	v_cmp_gt_i32_e64 s[58:59], v50, v46
	v_cmp_gt_i32_e64 s[60:61], v51, v46
	v_cmp_gt_i32_e64 s[62:63], v53, v46
	v_or_b32_e32 v46, v48, v1
	s_add_u32 s5, s84, s6
	ds_read2_b32 v[38:39], v38 offset1:16
	v_mul_u32_u24_e32 v125, 0x90, v46
	v_or_b32_e32 v46, 32, v48
	s_addc_u32 s7, 0, s7
	s_lshl_b32 s6, s90, 7
	v_or_b32_e32 v1, v46, v1
	s_add_u32 s6, s6, s5
	v_mul_u32_u24_e32 v129, 0x90, v1
	v_lshlrev_b64 v[44:45], 11, v[44:45]
	s_addc_u32 s7, 0, s7
	v_and_b32_e32 v1, 7, v42
	v_bitop3_b32 v122, v47, v43, 24 bitop3:0x6c
	v_bitop3_b32 v126, v48, v43, 32 bitop3:0x36
	v_bitop3_b32 v130, v43, v48, 32 bitop3:0x36
	v_bitop3_b32 v132, v48, v43, 32 bitop3:0x14
	v_lshl_add_u64 v[44:45], s[6:7], 0, v[44:45]
	v_lshlrev_b32_e32 v42, 4, v1
	v_mov_b32_e32 v43, v0
	v_readlane_b32 s6, v255, 21
	v_or_b32_e32 v47, v46, v49
	v_lshl_add_u64 v[42:43], v[44:45], 0, v[42:43]
	v_readlane_b32 s7, v255, 22
	v_mov_b32_e32 v44, v0
	v_mov_b32_e32 v45, v0
	v_add_u32_e32 v120, 0, v34
	s_waitcnt lgkmcnt(0)
	v_sub_f32_e32 v34, v38, v36
	v_sub_f32_e32 v36, v39, v40
	v_cmp_gt_i32_e64 s[56:57], v54, v52
	v_cmp_gt_i32_e64 s[66:67], v50, v52
	v_cmp_gt_i32_e64 s[68:69], v51, v52
	v_cmp_gt_i32_e64 s[70:71], v53, v52
	v_mul_u32_u24_e32 v127, 0x90, v47
	v_lshl_add_u64 v[112:113], s[6:7], 0, v[42:43]
	v_mov_b32_e32 v1, v0
	v_mov_b32_e32 v42, v0
	v_mov_b32_e32 v43, v0
	v_mov_b64_e32 v[60:61], v[44:45]
	v_mov_b64_e32 v[48:49], v[44:45]
	v_mov_b64_e32 v[64:65], v[44:45]
	v_mov_b64_e32 v[52:53], v[44:45]
	v_mov_b64_e32 v[68:69], v[44:45]
	v_mov_b64_e32 v[56:57], v[44:45]
	v_mov_b64_e32 v[72:73], v[44:45]
	s_mov_b32 s3, s79
	s_mov_b32 s74, 2
	s_mov_b32 s33, 0
	v_cmp_eq_u32_e64 s[8:9], 0, v35
	v_mov_b32_e32 v35, v34
	v_mov_b32_e32 v38, v34
	v_mov_b32_e32 v37, v34
	v_mov_b32_e32 v39, v36
	v_mov_b32_e32 v40, v36
	v_mov_b32_e32 v41, v36
	v_xor_b32_e32 v124, 16, v122
	v_xor_b32_e32 v128, 16, v126
	v_xor_b32_e32 v131, 16, v130
	v_xor_b32_e32 v133, 16, v132
	s_lshl_b32 s5, s86, 10
	s_sub_i32 s79, 0, s4
	s_mov_b64 s[6:7], 0
	v_mov_b32_e32 v135, 0xfffffc00
	v_mov_b32_e32 v134, 0
	v_mov_b32_e32 v136, v120
	v_mov_b64_e32 v[58:59], v[42:43]
	v_mov_b64_e32 v[46:47], v[42:43]
	v_mov_b64_e32 v[62:63], v[42:43]
	v_mov_b64_e32 v[50:51], v[42:43]
	v_mov_b64_e32 v[66:67], v[42:43]
	v_mov_b64_e32 v[54:55], v[42:43]
	v_mov_b64_e32 v[70:71], v[42:43]
	v_mov_b64_e32 v[110:111], v[0:1]
	v_lshl_add_u32 v212, v122, 1, v123
	v_lshl_add_u32 v213, v124, 1, v123
	v_lshl_add_u32 v214, v122, 1, v125
	v_lshl_add_u32 v215, v124, 1, v125
	v_lshl_add_u32 v216, v126, 1, v127
	v_lshl_add_u32 v217, v128, 1, v127
	v_lshl_add_u32 v218, v126, 1, v129
	v_lshl_add_u32 v219, v128, 1, v129
	v_lshl_add_u32 v220, v130, 1, v123
	v_lshl_add_u32 v221, v131, 1, v123
	v_lshl_add_u32 v222, v130, 1, v125
	v_lshl_add_u32 v223, v131, 1, v125
	v_lshl_add_u32 v236, v132, 1, v127
	v_lshl_add_u32 v237, v133, 1, v127
	v_lshl_add_u32 v238, v132, 1, v129
	v_lshl_add_u32 v239, v133, 1, v129
	s_branch .LBB0_533

; #define LAS __attribute__((address_space(3)))
; template <bool MOBA>
; __device__ __forceinline__ void attn_unit(unsigned char* lds, LAS unsigned char* lds3, const Params& p, int b, int h, int qb) {
;     ...
;                 const float f0 = fq2[0] - mref[0], f1 = fq2[1] - mref[1];
; #pragma unroll
;                 for (int kb = 0; kb < 4; ++kb) { const f32x4 fk = *(const LAS f32x4*)(Fs + 64 * t + 16 * kb + 4 * fq); s[kb][0] = f0 - fk; s[kb][1] = f1 - fk; }
;             } else {
;                 band = (t >> 2) >= qb - 1;
;                 const float cc = band ? 0.f : c31;
;                 const float c0 = (qv[0] ? cc : NEGBIG) - mrc[0], c1 = (qv[1] ? cc : NEGBIG) - mrc[1];
; #pragma unroll
;                 for (int kb = 0; kb < 4; ++kb) { s[kb][0] = (f32x4){c0, c0, c0, c0}; s[kb][1] = (f32x4){c1, c1, c1, c1}; }
;             }
;             { bf16x8 kf[4][2];
; #pragma unroll
;             for (int kb = 0; kb < 4; ++kb)
; #pragma unroll
;                 for (int ks = 0; ks < 2; ++ks) kf[kb][ks] = *(const LAS bf16x8*)(Ks + slot * 4608 + (16 * kb + fr) * 72 + 32 * ks + 8 * fq);
;             __builtin_amdgcn_sched_barrier(0);
; #pragma unroll
;             for (int kb = 0; kb < 4; ++kb)
; #pragma unroll
;                 for (int ks = 0; ks < 2; ++ks) {
;                     s[kb][0] = __builtin_amdgcn_mfma_f32_16x16x32_bf16(kf[kb][ks], qf[0][ks], s[kb][0], 0, 0, 0); s[kb][1] = __builtin_amdgcn_mfma_f32_16x16x32_bf16(kf[kb][ks], qf[1][ks], s[kb][1], 0, 0, 0); }
;             __builtin_amdgcn_sched_barrier(0); }
;             if (MOBA && band) {
;                 asm volatile("" ::: "memory");
; #pragma unroll
;                 for (int kb = 0; kb < 4; ++kb)
; #pragma unroll
;                     for (int jb = 0; jb < 2; ++jb)
; #pragma unroll
;                         for (int r = 0; r < 4; ++r) { int d = (256 * qb + qpl[jb]) - (64 * t + 16 * kb + 4 * fq + r); d = d < 0 ? 0 : (d > 127 ? 127 : d); s[kb][jb][r] += tbl[d]; }
;             }
;             if (diag) {
;                 asm volatile("" ::: "memory");
; #pragma unroll
;                 for (int kb = 0; kb < 4; ++kb)
; #pragma unroll
;                     for (int jb = 0; jb < 2; ++jb)
; #pragma unroll
;                         for (int r = 0; r < 4; ++r) { if ((64 * tl + 16 * kb + 4 * fq + r) > (MOBA ? qpl[jb] : qloc + 16 * jb)) s[kb][jb][r] = NEGBIG; }
;             }
.LBB0_539:
	s_and_b32 s33, s33, 1
	s_add_i32 s84, s79, s74
	s_add_i32 s94, s74, 1
	s_cmp_gt_i32 s94, s4
	s_cselect_b64 vcc, -1, 0
	s_or_b64 vcc, vcc, s[6:7]
	s_mul_i32 s94, s33, 0x4800
	s_and_b64 vcc, exec, vcc
	v_add_u32_e32 v137, s5, v136
	v_add3_u32 v1, v120, s94, v121
	s_cbranch_vccnz .LBB0_543
	v_add_u32_e32 v86, 0x12380, v137
	ds_read_b128 v[86:89], v86
	v_add_u32_e32 v74, 0x12300, v137
	v_add_u32_e32 v82, 0x12340, v137
	ds_read_b128 v[74:77], v74
	ds_read_b128 v[82:85], v82
	s_waitcnt lgkmcnt(2)
	v_pk_add_f32 v[94:95], v[34:35], v[86:87] neg_lo:[0,1] neg_hi:[0,1]
	v_pk_add_f32 v[140:141], v[40:41], v[86:87] neg_lo:[0,1] neg_hi:[0,1]
	v_add_u32_e32 v86, 0x123c0, v137
	v_pk_add_f32 v[96:97], v[34:35], v[88:89] neg_lo:[0,1] neg_hi:[0,1]
	v_pk_add_f32 v[142:143], v[40:41], v[88:89] neg_lo:[0,1] neg_hi:[0,1]
	ds_read_b128 v[86:89], v86
	s_waitcnt lgkmcnt(2)
	v_pk_add_f32 v[80:81], v[34:35], v[76:77] neg_lo:[0,1] neg_hi:[0,1]
	v_pk_add_f32 v[78:79], v[34:35], v[74:75] neg_lo:[0,1] neg_hi:[0,1]
	s_waitcnt lgkmcnt(0)
	v_pk_add_f32 v[146:147], v[34:35], v[88:89] neg_lo:[0,1] neg_hi:[0,1]
	v_pk_add_f32 v[144:145], v[34:35], v[86:87] neg_lo:[0,1] neg_hi:[0,1]
	v_pk_add_f32 v[150:151], v[40:41], v[88:89] neg_lo:[0,1] neg_hi:[0,1]
	v_pk_add_f32 v[148:149], v[40:41], v[86:87] neg_lo:[0,1] neg_hi:[0,1]
	ds_read_b128 v[86:89], v1
	ds_read_b128 v[98:101], v1 offset:64
	ds_read_b128 v[152:155], v1 offset:2304
	ds_read_b128 v[156:159], v1 offset:2368
	ds_read_b128 v[160:163], v1 offset:4608
	ds_read_b128 v[164:167], v1 offset:4672
	ds_read_b128 v[168:171], v1 offset:6912
	ds_read_b128 v[180:183], v1 offset:6976
	v_pk_add_f32 v[76:77], v[40:41], v[76:77] neg_lo:[0,1] neg_hi:[0,1]
	v_pk_add_f32 v[74:75], v[40:41], v[74:75] neg_lo:[0,1] neg_hi:[0,1]
	v_pk_add_f32 v[92:93], v[34:35], v[84:85] neg_lo:[0,1] neg_hi:[0,1]
	v_pk_add_f32 v[90:91], v[34:35], v[82:83] neg_lo:[0,1] neg_hi:[0,1]
	v_pk_add_f32 v[84:85], v[40:41], v[84:85] neg_lo:[0,1] neg_hi:[0,1]
	v_pk_add_f32 v[82:83], v[40:41], v[82:83] neg_lo:[0,1] neg_hi:[0,1]
	s_waitcnt lgkmcnt(7)
	v_mfma_f32_16x16x32_bf16 v[78:81], v[86:89], v[6:9], v[78:81]
	s_cmp_lg_u32 s84, -1
	v_mfma_f32_16x16x32_bf16 v[74:77], v[86:89], v[18:21], v[74:77]
	s_waitcnt lgkmcnt(6)
	v_mfma_f32_16x16x32_bf16 v[102:105], v[98:101], v[10:13], v[78:81]
	v_mfma_f32_16x16x32_bf16 v[86:89], v[98:101], v[22:25], v[74:77]
	s_waitcnt lgkmcnt(5)
	v_mfma_f32_16x16x32_bf16 v[74:77], v[152:155], v[6:9], v[90:93]
	v_mfma_f32_16x16x32_bf16 v[78:81], v[152:155], v[18:21], v[82:85]
	s_waitcnt lgkmcnt(4)
	v_mfma_f32_16x16x32_bf16 v[98:101], v[156:159], v[10:13], v[74:77]
	v_mfma_f32_16x16x32_bf16 v[82:85], v[156:159], v[22:25], v[78:81]
	s_waitcnt lgkmcnt(3)
	v_mfma_f32_16x16x32_bf16 v[74:77], v[160:163], v[6:9], v[94:97]
	v_mfma_f32_16x16x32_bf16 v[78:81], v[160:163], v[18:21], v[140:143]
	s_waitcnt lgkmcnt(2)
	v_mfma_f32_16x16x32_bf16 v[94:97], v[164:167], v[10:13], v[74:77]
	v_mfma_f32_16x16x32_bf16 v[74:77], v[164:167], v[22:25], v[78:81]
	s_waitcnt lgkmcnt(1)
	v_mfma_f32_16x16x32_bf16 v[78:81], v[168:171], v[6:9], v[144:147]
	v_mfma_f32_16x16x32_bf16 v[140:143], v[168:171], v[18:21], v[148:151]
	s_waitcnt lgkmcnt(0)
	v_mfma_f32_16x16x32_bf16 v[90:93], v[180:183], v[10:13], v[78:81]
	v_mfma_f32_16x16x32_bf16 v[78:81], v[180:183], v[22:25], v[140:143]
	s_cbranch_scc1 .LBB0_542
	s_nop 3
	v_mov_b32_e32 v140, s93
	v_cndmask_b32_e64 v139, v102, v140, s[10:11]
	v_cndmask_b32_e64 v102, v139, v102, s[12:13]
	v_cndmask_b32_e64 v139, v86, v140, s[18:19]
	v_cndmask_b32_e64 v103, v226, v103, s[12:13]
	v_cndmask_b32_e64 v104, v104, v226, s[14:15]
	v_cndmask_b32_e64 v105, v105, v226, s[16:17]
	v_cndmask_b32_e64 v87, v226, v87, s[20:21]
	v_cndmask_b32_e64 v86, v139, v86, s[20:21]
	v_cndmask_b32_e64 v88, v88, v226, s[22:23]
	v_cndmask_b32_e64 v89, v89, v226, s[24:25]
	v_cndmask_b32_e64 v98, v98, v140, s[26:27]
	v_cndmask_b32_e64 v99, v99, v226, s[28:29]
	v_cndmask_b32_e64 v100, v100, v226, s[30:31]
	v_cndmask_b32_e64 v101, v101, v226, s[34:35]
	v_cndmask_b32_e64 v82, v82, v140, s[10:11]
	v_cndmask_b32_e64 v83, v83, v226, s[36:37]
	v_cndmask_b32_e64 v84, v84, v226, s[38:39]
	v_cndmask_b32_e64 v85, v85, v226, s[40:41]
	v_cndmask_b32_e64 v94, v94, v140, s[42:43]
	v_cndmask_b32_e64 v95, v95, v226, s[44:45]
	v_cndmask_b32_e64 v96, v96, v226, s[46:47]
	v_cndmask_b32_e64 v97, v97, v226, s[48:49]
	v_cndmask_b32_e64 v74, v74, v140, s[50:51]
	v_cndmask_b32_e64 v75, v75, v226, s[52:53]
	v_cndmask_b32_e64 v76, v76, v226, s[54:55]
	v_cndmask_b32_e64 v77, v77, v226, s[56:57]
	v_cndmask_b32_e64 v90, v90, v140, s[58:59]
	v_cndmask_b32_e64 v91, v91, v226, s[60:61]
	v_cndmask_b32_e64 v92, v92, v226, s[62:63]
	v_cndmask_b32_e64 v93, v93, v226, s[64:65]
	v_cndmask_b32_e64 v78, v78, v140, s[66:67]
	v_cndmask_b32_e64 v79, v79, v226, s[68:69]
	v_cndmask_b32_e64 v80, v80, v226, s[70:71]
	v_cndmask_b32_e64 v81, v81, v226, s[72:73]
; #define LAS __attribute__((address_space(3)))
; __device__ __forceinline__ unsigned pk2(float lo, float hi) { const f32x2_t v = {lo, hi}; const bf16x2_t b = __builtin_convertvector(v, bf16x2_t); return __builtin_bit_cast(unsigned, b); }
; template <bool MOBA>
; __device__ __forceinline__ void attn_unit(unsigned char* lds, LAS unsigned char* lds3, const Params& p, int b, int h, int qb) {
;     ...
;             for (int jb = 0; jb < 2; ++jb) { float ls = 0.f;
; #pragma unroll
;                 for (int kb = 0; kb < 4; ++kb)
; #pragma unroll
;                     for (int r = 0; r < 4; ++r) { const float e = __builtin_amdgcn_exp2f(s[kb][jb][r]); s[kb][jb][r] = e; ls += e; }
;                 lrow[jb] += ls; }
;             { u32x2 vlo[2][4], vhi[2][4];
; #pragma unroll
;             for (int ks2 = 0; ks2 < 2; ++ks2)
; #pragma unroll
;                 for (int db = 0; db < 4; ++db) { const int d = 32 * (db >> 1) + 8 * (fr >> 2) + 4 * (db & 1) + (fr & 3);        const int kx = (32 * ks2 + 4 * fq) ^ (((d >> 3) & 7) << 3);
;                     vlo[ks2][db] = *(const LAS u32x2*)(Vt + slot * 4608 + d * 72 + kx); vhi[ks2][db] = *(const LAS u32x2*)(Vt + slot * 4608 + d * 72 + (kx ^ 16)); }
;             bf16x8 pf[2][2];
; #pragma unroll
;             for (int ks2 = 0; ks2 < 2; ++ks2)
; #pragma unroll
;                 for (int jb = 0; jb < 2; ++jb) { const f32x4 a = s[2 * ks2][jb], c = s[2 * ks2 + 1][jb]; u32x4 pw; pw.x = pk2(a[0], a[1]); pw.y = pk2(a[2], a[3]); pw.z = pk2(c[0], c[1]); pw.w = pk2(c[2], c[3]); pf[ks2][jb] = __builtin_bit_cast(bf16x8, pw); }
;             __builtin_amdgcn_sched_barrier(0);
; #pragma unroll
;             for (int ks2 = 0; ks2 < 2; ++ks2)
; #pragma unroll
;                 for (int db = 0; db < 4; ++db) { u32x4 vv; vv.x = vlo[ks2][db].x; vv.y = vlo[ks2][db].y; vv.z = vhi[ks2][db].x; vv.w = vhi[ks2][db].y; const bf16x8 vf = __builtin_bit_cast(bf16x8, vv);
;                     o[db][0] = __builtin_amdgcn_mfma_f32_16x16x32_bf16(vf, pf[ks2][0], o[db][0], 0, 0, 0); o[db][1] = __builtin_amdgcn_mfma_f32_16x16x32_bf16(vf, pf[ks2][1], o[db][1], 0, 0, 0); }
;             __builtin_amdgcn_sched_barrier(0); }
.LBB0_542:
	v_exp_f32_e32 v145, v102
	v_exp_f32_e32 v144, v86
	v_exp_f32_e32 v147, v103
	v_exp_f32_e32 v146, v87
	v_exp_f32_e32 v149, v104
	v_exp_f32_e32 v148, v88
	v_exp_f32_e32 v151, v105
	v_exp_f32_e32 v150, v89
	v_exp_f32_e32 v153, v98
	v_exp_f32_e32 v152, v82
	v_exp_f32_e32 v154, v83
	v_pk_add_f32 v[82:83], v[144:145], 0 op_sel_hi:[1,0]
	v_exp_f32_e32 v155, v99
	v_pk_add_f32 v[82:83], v[146:147], v[82:83]
	v_exp_f32_e32 v157, v100
	v_exp_f32_e32 v156, v84
	v_pk_add_f32 v[82:83], v[148:149], v[82:83]
	v_exp_f32_e32 v159, v101
	v_exp_f32_e32 v158, v85
	v_pk_add_f32 v[82:83], v[150:151], v[82:83]
	v_exp_f32_e32 v161, v94
	v_exp_f32_e32 v160, v74
	v_pk_add_f32 v[82:83], v[152:153], v[82:83]
	v_exp_f32_e32 v163, v95
	v_pk_add_f32 v[82:83], v[154:155], v[82:83]
	v_exp_f32_e32 v162, v75
	v_exp_f32_e32 v165, v96
	v_pk_add_f32 v[82:83], v[156:157], v[82:83]
	v_exp_f32_e32 v164, v76
	v_exp_f32_e32 v167, v97
	v_pk_add_f32 v[82:83], v[158:159], v[82:83]
	v_exp_f32_e32 v166, v77
	v_exp_f32_e32 v169, v90
	v_pk_add_f32 v[82:83], v[160:161], v[82:83]
	v_exp_f32_e32 v168, v78
	v_exp_f32_e32 v171, v91
	v_exp_f32_e32 v170, v79
	v_pk_add_f32 v[74:75], v[162:163], v[82:83]
	v_exp_f32_e32 v173, v92
	v_exp_f32_e32 v172, v80
	v_pk_add_f32 v[74:75], v[164:165], v[74:75]
	v_exp_f32_e32 v181, v93
	v_exp_f32_e32 v180, v81
	v_pk_add_f32 v[74:75], v[166:167], v[74:75]
	v_pk_add_f32 v[74:75], v[168:169], v[74:75]
	v_pk_add_f32 v[74:75], v[170:171], v[74:75]
	v_pk_add_f32 v[74:75], v[172:173], v[74:75]
	v_pk_add_f32 v[74:75], v[180:181], v[74:75]
	v_pk_add_f32 v[110:111], v[110:111], v[74:75]
	v_add_u32_e32 v74, s94, v212
	v_add_u32_e32 v76, s94, v213
	v_add_u32_e32 v78, s94, v214
	v_add_u32_e32 v80, s94, v215
	v_add_u32_e32 v82, s94, v216
	v_add_u32_e32 v84, s94, v217
	v_add_u32_e32 v86, s94, v218
	v_add_u32_e32 v88, s94, v219
	v_add_u32_e32 v90, s94, v220
	v_add_u32_e32 v92, s94, v221
	v_add_u32_e32 v94, s94, v222
	v_add_u32_e32 v96, s94, v223
	v_add_u32_e32 v98, s94, v236
	v_add_u32_e32 v100, s94, v237
	v_add_u32_e32 v102, s94, v238
	v_add_u32_e32 v104, s94, v239
	ds_read_b64 v[74:75], v74 offset:36864
	ds_read_b64 v[76:77], v76 offset:36864
	ds_read_b64 v[78:79], v78 offset:36864
	ds_read_b64 v[80:81], v80 offset:36864
	ds_read_b64 v[82:83], v82 offset:36864
	ds_read_b64 v[84:85], v84 offset:36864
	ds_read_b64 v[86:87], v86 offset:36864
	ds_read_b64 v[88:89], v88 offset:36864
	ds_read_b64 v[90:91], v90 offset:36864
	ds_read_b64 v[92:93], v92 offset:36864
	ds_read_b64 v[94:95], v94 offset:36864
	ds_read_b64 v[96:97], v96 offset:36864
	ds_read_b64 v[98:99], v98 offset:36864
	ds_read_b64 v[100:101], v100 offset:36864
	ds_read_b64 v[102:103], v102 offset:36864
	ds_read_b64 v[104:105], v104 offset:36864
	v_cvt_pk_bf16_f32 v140, v145, v147
	v_cvt_pk_bf16_f32 v141, v149, v151
	v_cvt_pk_bf16_f32 v142, v153, v155
	v_cvt_pk_bf16_f32 v143, v157, v159
	v_cvt_pk_bf16_f32 v144, v144, v146
	v_cvt_pk_bf16_f32 v145, v148, v150
	v_cvt_pk_bf16_f32 v146, v152, v154
	v_cvt_pk_bf16_f32 v147, v156, v158
	v_cvt_pk_bf16_f32 v148, v161, v163
	v_cvt_pk_bf16_f32 v149, v165, v167
	v_cvt_pk_bf16_f32 v150, v169, v171
	v_cvt_pk_bf16_f32 v151, v173, v181
	v_cvt_pk_bf16_f32 v152, v160, v162
	v_cvt_pk_bf16_f32 v153, v164, v166
	v_cvt_pk_bf16_f32 v154, v168, v170
	v_cvt_pk_bf16_f32 v155, v172, v180
	s_waitcnt lgkmcnt(14)
	v_mfma_f32_16x16x32_bf16 v[70:73], v[74:77], v[140:143], v[70:73]
	v_mfma_f32_16x16x32_bf16 v[54:57], v[74:77], v[144:147], v[54:57]
	s_waitcnt lgkmcnt(12)
	v_mfma_f32_16x16x32_bf16 v[66:69], v[78:81], v[140:143], v[66:69]
	v_mfma_f32_16x16x32_bf16 v[50:53], v[78:81], v[144:147], v[50:53]
	s_waitcnt lgkmcnt(10)
	v_mfma_f32_16x16x32_bf16 v[62:65], v[82:85], v[140:143], v[62:65]
	v_mfma_f32_16x16x32_bf16 v[46:49], v[82:85], v[144:147], v[46:49]
	s_waitcnt lgkmcnt(8)
	v_mfma_f32_16x16x32_bf16 v[58:61], v[86:89], v[140:143], v[58:61]
	v_mfma_f32_16x16x32_bf16 v[42:45], v[86:89], v[144:147], v[42:45]
	s_waitcnt lgkmcnt(6)
	v_mfma_f32_16x16x32_bf16 v[70:73], v[90:93], v[148:151], v[70:73]
	v_mfma_f32_16x16x32_bf16 v[54:57], v[90:93], v[152:155], v[54:57]
	s_waitcnt lgkmcnt(4)
	v_mfma_f32_16x16x32_bf16 v[66:69], v[94:97], v[148:151], v[66:69]
	v_mfma_f32_16x16x32_bf16 v[50:53], v[94:97], v[152:155], v[50:53]
	s_waitcnt lgkmcnt(2)
	v_mfma_f32_16x16x32_bf16 v[62:65], v[98:101], v[148:151], v[62:65]
	v_mfma_f32_16x16x32_bf16 v[46:49], v[98:101], v[152:155], v[46:49]
	s_waitcnt lgkmcnt(0)
	v_mfma_f32_16x16x32_bf16 v[58:61], v[102:105], v[148:151], v[58:61]
	v_mfma_f32_16x16x32_bf16 v[42:45], v[102:105], v[152:155], v[42:45]

; #define LAS __attribute__((address_space(3)))
; template <bool MOBA>
; __device__ __forceinline__ void attn_unit(unsigned char* lds, LAS unsigned char* lds3, const Params& p, int b, int h, int qb) {
;     ...
;             const bool diag = (tl == (w >> 1));
;             f32x4 s[4][2];
;             bool band = false;
;             if (!MOBA) {
;                 const float f0 = fq2[0] - mref[0], f1 = fq2[1] - mref[1];
; #pragma unroll
;                 for (int kb = 0; kb < 4; ++kb) { const f32x4 fk = *(const LAS f32x4*)(Fs + 64 * t + 16 * kb + 4 * fq); s[kb][0] = f0 - fk; s[kb][1] = f1 - fk; }
;             } else {
;                 band = (t >> 2) >= qb - 1;
;                 const float cc = band ? 0.f : c31;
;                 const float c0 = (qv[0] ? cc : NEGBIG) - mrc[0], c1 = (qv[1] ? cc : NEGBIG) - mrc[1];
; #pragma unroll
;                 for (int kb = 0; kb < 4; ++kb) { s[kb][0] = (f32x4){c0, c0, c0, c0}; s[kb][1] = (f32x4){c1, c1, c1, c1}; }
;             }
;             { bf16x8 kf[4][2];
; #pragma unroll
;             for (int kb = 0; kb < 4; ++kb)
; #pragma unroll
;                 for (int ks = 0; ks < 2; ++ks) kf[kb][ks] = *(const LAS bf16x8*)(Ks + slot * 4608 + (16 * kb + fr) * 72 + 32 * ks + 8 * fq);
;             __builtin_amdgcn_sched_barrier(0);
; #pragma unroll
;             for (int kb = 0; kb < 4; ++kb)
; #pragma unroll
;                 for (int ks = 0; ks < 2; ++ks) {
;                     s[kb][0] = __builtin_amdgcn_mfma_f32_16x16x32_bf16(kf[kb][ks], qf[0][ks], s[kb][0], 0, 0, 0); s[kb][1] = __builtin_amdgcn_mfma_f32_16x16x32_bf16(kf[kb][ks], qf[1][ks], s[kb][1], 0, 0, 0); }
;             __builtin_amdgcn_sched_barrier(0); }
;             if (MOBA && band) {
;                 asm volatile("" ::: "memory");
; #pragma unroll
;                 for (int kb = 0; kb < 4; ++kb)
; #pragma unroll
;                     for (int jb = 0; jb < 2; ++jb)
; #pragma unroll
;                         for (int r = 0; r < 4; ++r) { int d = (256 * qb + qpl[jb]) - (64 * t + 16 * kb + 4 * fq + r); d = d < 0 ? 0 : (d > 127 ? 127 : d); s[kb][jb][r] += tbl[d]; }
;             }
;             if (diag) {
;                 asm volatile("" ::: "memory");
; #pragma unroll
;                 for (int kb = 0; kb < 4; ++kb)
; #pragma unroll
;                     for (int jb = 0; jb < 2; ++jb)
; #pragma unroll
.LBB0_546:
	s_cmp_gt_i32 s74, s4
	s_cselect_b64 vcc, -1, 0
	s_or_b64 vcc, vcc, s[6:7]
	s_and_b64 vcc, exec, vcc
	s_cbranch_vccnz .LBB0_553
	v_add_u32_e32 v86, 0x12280, v137
	ds_read_b128 v[86:89], v86
	v_add_u32_e32 v74, 0x12200, v137
	v_add_u32_e32 v82, 0x12240, v137
	ds_read_b128 v[74:77], v74
	ds_read_b128 v[82:85], v82
	s_waitcnt lgkmcnt(2)
	v_pk_add_f32 v[94:95], v[34:35], v[86:87] neg_lo:[0,1] neg_hi:[0,1]
	v_pk_add_f32 v[138:139], v[40:41], v[86:87] neg_lo:[0,1] neg_hi:[0,1]
	v_add_u32_e32 v86, 0x122c0, v137
	v_pk_add_f32 v[96:97], v[34:35], v[88:89] neg_lo:[0,1] neg_hi:[0,1]
	v_pk_add_f32 v[140:141], v[40:41], v[88:89] neg_lo:[0,1] neg_hi:[0,1]
	ds_read_b128 v[86:89], v86
	s_waitcnt lgkmcnt(2)
	v_pk_add_f32 v[80:81], v[34:35], v[76:77] neg_lo:[0,1] neg_hi:[0,1]
	v_pk_add_f32 v[78:79], v[34:35], v[74:75] neg_lo:[0,1] neg_hi:[0,1]
	s_waitcnt lgkmcnt(0)
	v_pk_add_f32 v[144:145], v[34:35], v[88:89] neg_lo:[0,1] neg_hi:[0,1]
	v_pk_add_f32 v[142:143], v[34:35], v[86:87] neg_lo:[0,1] neg_hi:[0,1]
	v_pk_add_f32 v[148:149], v[40:41], v[88:89] neg_lo:[0,1] neg_hi:[0,1]
	v_pk_add_f32 v[146:147], v[40:41], v[86:87] neg_lo:[0,1] neg_hi:[0,1]
	ds_read_b128 v[86:89], v1 offset:9216
	ds_read_b128 v[98:101], v1 offset:9280
	ds_read_b128 v[150:153], v1 offset:11520
	ds_read_b128 v[154:157], v1 offset:11584
	ds_read_b128 v[158:161], v1 offset:13824
	ds_read_b128 v[162:165], v1 offset:13888
	ds_read_b128 v[166:169], v1 offset:16128
	ds_read_b128 v[170:173], v1 offset:16192
	v_pk_add_f32 v[76:77], v[40:41], v[76:77] neg_lo:[0,1] neg_hi:[0,1]
	v_pk_add_f32 v[74:75], v[40:41], v[74:75] neg_lo:[0,1] neg_hi:[0,1]
	v_pk_add_f32 v[92:93], v[34:35], v[84:85] neg_lo:[0,1] neg_hi:[0,1]
	v_pk_add_f32 v[90:91], v[34:35], v[82:83] neg_lo:[0,1] neg_hi:[0,1]
	v_pk_add_f32 v[84:85], v[40:41], v[84:85] neg_lo:[0,1] neg_hi:[0,1]
	v_pk_add_f32 v[82:83], v[40:41], v[82:83] neg_lo:[0,1] neg_hi:[0,1]
	s_waitcnt lgkmcnt(7)
	v_mfma_f32_16x16x32_bf16 v[74:77], v[86:89], v[18:21], v[74:77]
	s_cmp_lg_u32 s84, 0
	v_mfma_f32_16x16x32_bf16 v[78:81], v[86:89], v[6:9], v[78:81]
	s_waitcnt lgkmcnt(6)
	v_mfma_f32_16x16x32_bf16 v[86:89], v[98:101], v[22:25], v[74:77]
	s_waitcnt lgkmcnt(5)
	v_mfma_f32_16x16x32_bf16 v[74:77], v[150:153], v[6:9], v[90:93]
	v_mfma_f32_16x16x32_bf16 v[102:105], v[98:101], v[10:13], v[78:81]
	v_mfma_f32_16x16x32_bf16 v[78:81], v[150:153], v[18:21], v[82:85]
	s_waitcnt lgkmcnt(4)
	v_mfma_f32_16x16x32_bf16 v[98:101], v[154:157], v[10:13], v[74:77]
	s_waitcnt lgkmcnt(3)
	v_mfma_f32_16x16x32_bf16 v[74:77], v[158:161], v[6:9], v[94:97]
	v_mfma_f32_16x16x32_bf16 v[82:85], v[158:161], v[18:21], v[138:141]
	s_waitcnt lgkmcnt(2)
	v_mfma_f32_16x16x32_bf16 v[94:97], v[162:165], v[10:13], v[74:77]
	v_mfma_f32_16x16x32_bf16 v[74:77], v[162:165], v[22:25], v[82:85]
	s_waitcnt lgkmcnt(1)
	v_mfma_f32_16x16x32_bf16 v[82:85], v[166:169], v[6:9], v[142:145]
	v_mfma_f32_16x16x32_bf16 v[138:141], v[166:169], v[18:21], v[146:149]
	v_mfma_f32_16x16x32_bf16 v[78:81], v[154:157], v[22:25], v[78:81]
	s_waitcnt lgkmcnt(0)
	v_mfma_f32_16x16x32_bf16 v[90:93], v[170:173], v[10:13], v[82:85]
	v_mfma_f32_16x16x32_bf16 v[82:85], v[170:173], v[22:25], v[138:141]
	s_cbranch_scc1 .LBB0_549
	s_nop 2
	v_mov_b32_e32 v138, s93
	v_cndmask_b32_e64 v1, v102, v138, s[10:11]
	v_cndmask_b32_e64 v102, v1, v102, s[12:13]
	v_cndmask_b32_e64 v1, v86, v138, s[18:19]
	v_cndmask_b32_e64 v103, v226, v103, s[12:13]
	v_cndmask_b32_e64 v104, v104, v226, s[14:15]
	v_cndmask_b32_e64 v105, v105, v226, s[16:17]
	v_cndmask_b32_e64 v87, v226, v87, s[20:21]
	v_cndmask_b32_e64 v86, v1, v86, s[20:21]
	v_cndmask_b32_e64 v88, v88, v226, s[22:23]
	v_cndmask_b32_e64 v89, v89, v226, s[24:25]
	v_cndmask_b32_e64 v98, v98, v138, s[26:27]
	v_cndmask_b32_e64 v99, v99, v226, s[28:29]
	v_cndmask_b32_e64 v100, v100, v226, s[30:31]
	v_cndmask_b32_e64 v101, v101, v226, s[34:35]
	v_cndmask_b32_e64 v78, v78, v138, s[10:11]
	v_cndmask_b32_e64 v79, v79, v226, s[36:37]
	v_cndmask_b32_e64 v80, v80, v226, s[38:39]
	v_cndmask_b32_e64 v81, v81, v226, s[40:41]
	v_cndmask_b32_e64 v94, v94, v138, s[42:43]
	v_cndmask_b32_e64 v95, v95, v226, s[44:45]
	v_cndmask_b32_e64 v96, v96, v226, s[46:47]
	v_cndmask_b32_e64 v97, v97, v226, s[48:49]
	v_cndmask_b32_e64 v74, v74, v138, s[50:51]
	v_cndmask_b32_e64 v75, v75, v226, s[52:53]
	v_cndmask_b32_e64 v76, v76, v226, s[54:55]
	v_cndmask_b32_e64 v77, v77, v226, s[56:57]
	v_cndmask_b32_e64 v90, v90, v138, s[58:59]
	v_cndmask_b32_e64 v91, v91, v226, s[60:61]
	v_cndmask_b32_e64 v92, v92, v226, s[62:63]
	v_cndmask_b32_e64 v93, v93, v226, s[64:65]
	v_cndmask_b32_e64 v82, v82, v138, s[66:67]
	v_cndmask_b32_e64 v83, v83, v226, s[68:69]
	v_cndmask_b32_e64 v84, v84, v226, s[70:71]
	v_cndmask_b32_e64 v85, v85, v226, s[72:73]
; #define LAS __attribute__((address_space(3)))
; __device__ __forceinline__ unsigned pk2(float lo, float hi) { const f32x2_t v = {lo, hi}; const bf16x2_t b = __builtin_convertvector(v, bf16x2_t); return __builtin_bit_cast(unsigned, b); }
; template <bool MOBA>
; __device__ __forceinline__ void attn_unit(unsigned char* lds, LAS unsigned char* lds3, const Params& p, int b, int h, int qb) {
;     ...
;             {
; #pragma unroll
;             for (int jb = 0; jb < 2; ++jb) { float ls = 0.f;
; #pragma unroll
;                 for (int kb = 0; kb < 4; ++kb)
; #pragma unroll
;                     for (int r = 0; r < 4; ++r) { const float e = __builtin_amdgcn_exp2f(s[kb][jb][r]); s[kb][jb][r] = e; ls += e; }
;                 lrow[jb] += ls; }
;             { u32x2 vlo[2][4], vhi[2][4];
; #pragma unroll
;             for (int ks2 = 0; ks2 < 2; ++ks2)
; #pragma unroll
;                 for (int db = 0; db < 4; ++db) { const int d = 32 * (db >> 1) + 8 * (fr >> 2) + 4 * (db & 1) + (fr & 3);        const int kx = (32 * ks2 + 4 * fq) ^ (((d >> 3) & 7) << 3);
;                     vlo[ks2][db] = *(const LAS u32x2*)(Vt + slot * 4608 + d * 72 + kx); vhi[ks2][db] = *(const LAS u32x2*)(Vt + slot * 4608 + d * 72 + (kx ^ 16)); }
;             bf16x8 pf[2][2];
; #pragma unroll
;             for (int ks2 = 0; ks2 < 2; ++ks2)
; #pragma unroll
;                 for (int jb = 0; jb < 2; ++jb) { const f32x4 a = s[2 * ks2][jb], c = s[2 * ks2 + 1][jb]; u32x4 pw; pw.x = pk2(a[0], a[1]); pw.y = pk2(a[2], a[3]); pw.z = pk2(c[0], c[1]); pw.w = pk2(c[2], c[3]); pf[ks2][jb] = __builtin_bit_cast(bf16x8, pw); }
;             __builtin_amdgcn_sched_barrier(0);
; #pragma unroll
;             for (int ks2 = 0; ks2 < 2; ++ks2)
; #pragma unroll
;                 for (int db = 0; db < 4; ++db) { u32x4 vv; vv.x = vlo[ks2][db].x; vv.y = vlo[ks2][db].y; vv.z = vhi[ks2][db].x; vv.w = vhi[ks2][db].y; const bf16x8 vf = __builtin_bit_cast(bf16x8, vv);
;                     o[db][0] = __builtin_amdgcn_mfma_f32_16x16x32_bf16(vf, pf[ks2][0], o[db][0], 0, 0, 0); o[db][1] = __builtin_amdgcn_mfma_f32_16x16x32_bf16(vf, pf[ks2][1], o[db][1], 0, 0, 0); }
;             __builtin_amdgcn_sched_barrier(0); }
.LBB0_549:
	v_exp_f32_e32 v143, v102
	v_exp_f32_e32 v142, v86
	v_exp_f32_e32 v145, v103
	v_exp_f32_e32 v144, v87
	v_exp_f32_e32 v147, v104
	v_exp_f32_e32 v146, v88
	v_exp_f32_e32 v149, v105
	v_exp_f32_e32 v148, v89
	v_exp_f32_e32 v151, v98
	v_exp_f32_e32 v150, v78
	v_exp_f32_e32 v152, v79
	v_pk_add_f32 v[78:79], v[142:143], 0 op_sel_hi:[1,0]
	v_exp_f32_e32 v153, v99
	v_pk_add_f32 v[78:79], v[144:145], v[78:79]
	v_exp_f32_e32 v155, v100
	v_exp_f32_e32 v154, v80
	v_pk_add_f32 v[78:79], v[146:147], v[78:79]
	v_exp_f32_e32 v157, v101
	v_pk_add_f32 v[78:79], v[148:149], v[78:79]
	v_exp_f32_e32 v156, v81
	v_exp_f32_e32 v159, v94
	v_pk_add_f32 v[78:79], v[150:151], v[78:79]
	v_exp_f32_e32 v158, v74
	v_exp_f32_e32 v161, v95
	v_pk_add_f32 v[78:79], v[152:153], v[78:79]
	v_exp_f32_e32 v160, v75
	v_exp_f32_e32 v163, v96
	v_pk_add_f32 v[78:79], v[154:155], v[78:79]
	v_exp_f32_e32 v162, v76
	v_exp_f32_e32 v165, v97
	v_exp_f32_e32 v164, v77
	v_pk_add_f32 v[74:75], v[156:157], v[78:79]
	v_exp_f32_e32 v167, v90
	v_exp_f32_e32 v166, v82
	v_pk_add_f32 v[74:75], v[158:159], v[74:75]
	v_exp_f32_e32 v169, v91
	v_exp_f32_e32 v168, v83
	v_pk_add_f32 v[74:75], v[160:161], v[74:75]
	v_exp_f32_e32 v171, v92
	v_exp_f32_e32 v170, v84
	v_pk_add_f32 v[74:75], v[162:163], v[74:75]
	v_exp_f32_e32 v173, v93
	v_exp_f32_e32 v172, v85
	v_pk_add_f32 v[74:75], v[164:165], v[74:75]
	v_pk_add_f32 v[74:75], v[166:167], v[74:75]
	v_pk_add_f32 v[74:75], v[168:169], v[74:75]
	v_pk_add_f32 v[74:75], v[170:171], v[74:75]
	v_pk_add_f32 v[74:75], v[172:173], v[74:75]
	v_pk_add_f32 v[110:111], v[110:111], v[74:75]
	v_add_u32_e32 v74, s94, v212
	v_add_u32_e32 v76, s94, v213
	v_add_u32_e32 v78, s94, v214
	v_add_u32_e32 v80, s94, v215
	v_add_u32_e32 v82, s94, v216
	v_add_u32_e32 v84, s94, v217
	v_add_u32_e32 v86, s94, v218
	v_add_u32_e32 v88, s94, v219
	v_add_u32_e32 v90, s94, v220
	v_add_u32_e32 v92, s94, v221
	v_add_u32_e32 v94, s94, v222
	v_add_u32_e32 v96, s94, v223
	v_add_u32_e32 v98, s94, v236
	v_add_u32_e32 v100, s94, v237
	v_add_u32_e32 v102, s94, v238
	v_add_u32_e32 v104, s94, v239
	ds_read_b64 v[74:75], v74 offset:46080
	ds_read_b64 v[76:77], v76 offset:46080
	ds_read_b64 v[78:79], v78 offset:46080
	ds_read_b64 v[80:81], v80 offset:46080
	ds_read_b64 v[82:83], v82 offset:46080
	ds_read_b64 v[84:85], v84 offset:46080
	ds_read_b64 v[86:87], v86 offset:46080
	ds_read_b64 v[88:89], v88 offset:46080
	ds_read_b64 v[90:91], v90 offset:46080
	ds_read_b64 v[92:93], v92 offset:46080
	ds_read_b64 v[94:95], v94 offset:46080
	ds_read_b64 v[96:97], v96 offset:46080
	ds_read_b64 v[98:99], v98 offset:46080
	ds_read_b64 v[100:101], v100 offset:46080
	ds_read_b64 v[102:103], v102 offset:46080
	ds_read_b64 v[104:105], v104 offset:46080
	v_cvt_pk_bf16_f32 v138, v143, v145
	v_cvt_pk_bf16_f32 v139, v147, v149
	v_cvt_pk_bf16_f32 v140, v151, v153
	v_cvt_pk_bf16_f32 v141, v155, v157
	v_cvt_pk_bf16_f32 v142, v142, v144
	v_cvt_pk_bf16_f32 v143, v146, v148
	v_cvt_pk_bf16_f32 v144, v150, v152
	v_cvt_pk_bf16_f32 v145, v154, v156
	v_cvt_pk_bf16_f32 v146, v159, v161
	v_cvt_pk_bf16_f32 v147, v163, v165
	v_cvt_pk_bf16_f32 v148, v167, v169
	v_cvt_pk_bf16_f32 v149, v171, v173
	v_cvt_pk_bf16_f32 v150, v158, v160
	v_cvt_pk_bf16_f32 v151, v162, v164
	v_cvt_pk_bf16_f32 v152, v166, v168
	v_cvt_pk_bf16_f32 v153, v170, v172
	s_waitcnt lgkmcnt(14)
	v_mfma_f32_16x16x32_bf16 v[70:73], v[74:77], v[138:141], v[70:73]
	v_mfma_f32_16x16x32_bf16 v[54:57], v[74:77], v[142:145], v[54:57]
	s_waitcnt lgkmcnt(12)
	v_mfma_f32_16x16x32_bf16 v[66:69], v[78:81], v[138:141], v[66:69]
	v_mfma_f32_16x16x32_bf16 v[50:53], v[78:81], v[142:145], v[50:53]
	s_waitcnt lgkmcnt(10)
	v_mfma_f32_16x16x32_bf16 v[62:65], v[82:85], v[138:141], v[62:65]
	v_mfma_f32_16x16x32_bf16 v[46:49], v[82:85], v[142:145], v[46:49]
	s_waitcnt lgkmcnt(8)
	v_mfma_f32_16x16x32_bf16 v[58:61], v[86:89], v[138:141], v[58:61]
	v_mfma_f32_16x16x32_bf16 v[42:45], v[86:89], v[142:145], v[42:45]
	s_waitcnt lgkmcnt(6)
	v_mfma_f32_16x16x32_bf16 v[70:73], v[90:93], v[146:149], v[70:73]
	v_mfma_f32_16x16x32_bf16 v[54:57], v[90:93], v[150:153], v[54:57]
	s_waitcnt lgkmcnt(4)
	v_mfma_f32_16x16x32_bf16 v[66:69], v[94:97], v[146:149], v[66:69]
	v_mfma_f32_16x16x32_bf16 v[50:53], v[94:97], v[150:153], v[50:53]
	s_waitcnt lgkmcnt(2)
	v_mfma_f32_16x16x32_bf16 v[62:65], v[98:101], v[146:149], v[62:65]
	v_mfma_f32_16x16x32_bf16 v[46:49], v[98:101], v[150:153], v[46:49]
	s_waitcnt lgkmcnt(0)
	v_mfma_f32_16x16x32_bf16 v[58:61], v[102:105], v[146:149], v[58:61]
	v_mfma_f32_16x16x32_bf16 v[42:45], v[102:105], v[150:153], v[42:45]
	s_andn2_b64 vcc, exec, s[86:87]
	s_cbranch_vccz .LBB0_554
